# group barrier: returning arrival atomic (last arriver skips the poll); attention LDS-DMA statements no longer save/restore m0
# speedup vs baseline: 1.0047x; 1.0047x over previous
; #define WAIT_BAR(N) asm volatile("s_waitcnt vmcnt(" #N ") lgkmcnt(0)\n\ts_barrier":::"memory")
;   #define DMA_K(t,slot) glds16(ksrc+(long)(t)*KVBLK*DM,(unsigned)__builtin_amdgcn_readfirstlane(kdst+(slot)))
;   #define DMA_V(t,slot) do{ glds16(vsrc+(long)(t)*KVBLK*DM,(unsigned)__builtin_amdgcn_readfirstlane(vdst+2*(slot))); glds16(vsrc+(long)(t)*KVBLK*DM+64,(unsigned)__builtin_amdgcn_readfirstlane(vdst+2*(slot)+8192)); }while(0)
;   #define CMASK(P0,P1,t) do{int jb_=(t)-(NT-4); if(jb_>=0)cmask(P0,P1,jb_,qrel,hi);}while(0)
;   #define START(P0,P1) do{ const float rm=rowmax(P0,P1); resc=false; \
;     { const float dl=rm; mhat=fadd_s(mhat,dl); \
;       _Pragma("unroll") for(int r=0;r<16;++r){P0[r]=fsub_s(P0[r],dl);P1[r]=fsub_s(P1[r],dl);} \
;       _Pragma("unroll") for(int r=0;r<16;++r)negm[r]=-mhat; asm volatile("":"+v"(negm)); } \
;     _Pragma("unroll") for(int r=0;r<16;++r)P0[r]=__builtin_amdgcn_exp2f(P0[r]); }while(0)
;   #define CMASK(P0,P1,t) do{}while(0)
;   #define CMASK(P0,P1,t) do{int jb_=(t)-(NT-4); if(jb_>=0)cmask(P0,P1,jb_,qrel,hi);}while(0)
; template<int THRL> __device__ __forceinline__ void attn_unit(int b,int hq,int vcol,int qb,const bf16*Q,const bf16*__restrict__ K,const bf16*__restrict__ V,bf16*O,char*shm){
;     ...
;   const bf16*ksrc=Kh+(long)lane*DM+wid*8;
;   const bf16*vsrc=Vh+(long)(16*(wid&3)+(lane>>2))*DM+(wid>>2)*32+(lane&3)*8;
;   const unsigned kdst=lds0+LDS_K+wid*1024, vdst=lds0+LDS_V+wid*1024;
;     ...
;   const int vb0=(int)(lds0+LDS_V)+((lane>>4)&1)*32+(lane&3)*8+(4*hi+((lane&15)>>2))*64;
;   const char*Kbase=shm+LDS_K; bf16x8 kf[8];
;   const lds_cptr shm3=(lds_cptr)shm; const lds_cptr kp0=shm3+LDS_K+hi*1024+r32*16; const lds_cptr vp0=shm3+LDS_V+((lane>>4)&1)*32+(lane&3)*8+(4*hi+((lane&15)>>2))*64;
;   const int NT=(q0+QB)/KVBLK;
;   DMA_K(0,0);DMA_V(0,0);DMA_K(1,SLOTB);
;   bf16x8 qr[4];
;   #pragma unroll
;   for(int d0=0;d0<4;++d0)qr[d0]=*reinterpret_cast<const bf16x8*>(&Qw[(long)r32*DM+d0*16+hi*8]);
;   float mhat=0.f,l_reg=0.f;f32x16 o[4];o[0]=f32x16{};o[1]=f32x16{};o[2]=f32x16{};o[3]=f32x16{};f32x16 negm=f32x16{};asm volatile("":"+v"(negm));
;   const int qrel=wid*QBLK+r32;
;     ...
;   bool resc=false;
;     ...
;   f32x16 pA0,pA1,pB0,pB1;
;   int sl_prev=0,sl_cur=0,sl_next=SLOTB;
;     ...
;   DMA_K(2,2*SLOTB);
;   WAIT_BAR(4);
;   qkt(pA0,pA1,Kbase,qr,negm,r32,hi);asm volatile("s_nop 15\n\ts_nop 7":"+v"(pA0),"+v"(pA1));CMASK(pA0,pA1,0);
;   START(pA0,pA1);
.LBB0_258:
	v_mov_b32_e32 v36, v244
	s_mov_b32 s50, s92
	v_readfirstlane_b32 s33, v36
	s_ashr_i32 s65, s33, 6
	s_lshl_b32 s2, s65, 5
	s_ashr_i32 s3, s2, 31
	s_add_u32 s40, s2, s82
	s_addc_u32 s41, s3, 0
	s_lshl_b64 s[2:3], s[40:41], 11
	s_add_u32 s12, s6, s2
	s_addc_u32 s22, s7, s3
	s_or_b32 s90, s4, s79
	s_lshl_b64 s[2:3], s[90:91], 1
	s_add_u32 s24, s12, s2
	s_addc_u32 s25, s22, s3
	v_and_b32_e32 v250, 63, v36
	s_add_u32 s2, s83, s2
	s_addc_u32 s3, s1, s3
	v_lshlrev_b32_e32 v0, 11, v250
	v_lshl_add_u64 v[2:3], s[2:3], 0, v[0:1]
	s_lshl_b32 s2, s65, 3
	s_ashr_i32 s3, s2, 31
	v_lshl_add_u64 v[238:239], s[2:3], 1, v[2:3]
	s_lshl_b32 s2, s65, 4
	v_bfe_u32 v228, v36, 2, 4
	v_and_or_b32 v0, s2, 48, v228
	s_ashr_i32 s2, s33, 3
	s_and_b32 s92, s2, 0xffffffe0
	s_ashr_i32 s93, s92, 31
	s_lshl_b32 s2, s65, 10
	v_lshlrev_b32_e32 v0, 11, v0
	v_lshlrev_b32_e32 v246, 3, v36
	s_cmp_lg_u32 0, -1
	v_lshl_add_u64 v[2:3], s[34:35], 0, v[0:1]
	v_and_b32_e32 v247, 24, v246
	s_cselect_b32 s3, 0, 0
	v_lshl_add_u64 v[2:3], s[92:93], 1, v[2:3]
	v_lshlrev_b32_e32 v0, 1, v247
	s_add_i32 s22, s2, s3
	s_mov_b32 m0, s22
	s_nop 0
	global_load_lds_dwordx4 v[238:239], off
	v_and_b32_e32 v251, 31, v36
	v_lshl_add_u64 v[34:35], v[2:3], 0, v[0:1]
	s_add_i32 s23, s22, 0x6000
	s_mov_b32 m0, s23
	s_nop 0
	global_load_lds_dwordx4 v[34:35], off
	v_bfe_u32 v252, v36, 5, 1
	v_lshl_add_u64 v[2:3], v[34:35], 0, s[70:71]
	s_add_i32 s3, s22, 0x8000
	s_mov_b32 m0, s3
	s_nop 0
	global_load_lds_dwordx4 v[2:3], off
	v_lshlrev_b32_e32 v0, 11, v251
	v_lshl_add_u64 v[2:3], v[238:239], 0, s[94:95]
	s_add_i32 s3, s22, 0x2000
	s_mov_b32 m0, s3
	s_nop 0
	global_load_lds_dwordx4 v[2:3], off
	v_lshl_or_b32 v0, v252, 4, v0
	global_load_dwordx4 v[184:187], v0, s[24:25]
	global_load_dwordx4 v[176:179], v0, s[24:25] offset:32
	global_load_dwordx4 v[172:175], v0, s[24:25] offset:64
	global_load_dwordx4 v[164:167], v0, s[24:25] offset:96
	v_mov_b32_e32 v2, v1
	v_mov_b32_e32 v3, v1
	v_mov_b32_e32 v4, v1
	v_mov_b32_e32 v5, v1
	v_mov_b32_e32 v6, v1
	v_mov_b32_e32 v7, v1
	v_mov_b32_e32 v8, v1
	v_mov_b32_e32 v9, v1
	v_mov_b32_e32 v10, v1
	v_mov_b32_e32 v11, v1
	v_mov_b32_e32 v12, v1
	v_mov_b32_e32 v13, v1
	v_mov_b32_e32 v14, v1
	v_mov_b32_e32 v15, v1
	v_lshlrev_b32_e32 v0, 10, v252
	v_lshlrev_b32_e32 v16, 4, v251
	v_add3_u32 v232, 0, v0, v16
	v_mov_b32_e32 v0, v1
	v_mov_b64_e32 v[16:17], v[14:15]
	v_mov_b64_e32 v[14:15], v[12:13]
	v_mov_b64_e32 v[12:13], v[10:11]
	v_mov_b64_e32 v[10:11], v[8:9]
	v_mov_b64_e32 v[8:9], v[6:7]
	v_mov_b64_e32 v[6:7], v[4:5]
	v_mov_b64_e32 v[4:5], v[2:3]
	v_mov_b64_e32 v[2:3], v[0:1]
	v_lshl_add_u64 v[18:19], v[238:239], 0, s[8:9]
	s_add_i32 s3, s22, 0x4000
	s_mov_b32 m0, s3
	s_nop 0
	global_load_lds_dwordx4 v[18:19], off
	s_waitcnt vmcnt(4) lgkmcnt(0)
	s_barrier
	ds_read_b128 v[38:41], v232
	s_andn2_b64 vcc, exec, s[42:43]
	s_waitcnt vmcnt(3) lgkmcnt(0)
	v_mfma_f32_32x32x16_bf16 v[18:33], v[38:41], v[184:187], v[2:17]
	ds_read_b128 v[38:41], v232 offset:512
	s_waitcnt lgkmcnt(0)
	v_mfma_f32_32x32x16_bf16 v[2:17], v[38:41], v[184:187], v[2:17]
	ds_read_b128 v[38:41], v232 offset:2048
	s_waitcnt vmcnt(2) lgkmcnt(0)
	v_mfma_f32_32x32x16_bf16 v[18:33], v[38:41], v[176:179], v[18:33]
	ds_read_b128 v[38:41], v232 offset:2560
	s_waitcnt lgkmcnt(0)
	v_mfma_f32_32x32x16_bf16 v[2:17], v[38:41], v[176:179], v[2:17]
	ds_read_b128 v[38:41], v232 offset:4096
	s_waitcnt vmcnt(1) lgkmcnt(0)
	v_mfma_f32_32x32x16_bf16 v[18:33], v[38:41], v[172:175], v[18:33]
	ds_read_b128 v[38:41], v232 offset:4608
	s_waitcnt lgkmcnt(0)
	v_mfma_f32_32x32x16_bf16 v[2:17], v[38:41], v[172:175], v[2:17]
	ds_read_b128 v[38:41], v232 offset:6144
	s_waitcnt vmcnt(0) lgkmcnt(0)
	v_mfma_f32_32x32x16_bf16 v[18:33], v[38:41], v[164:167], v[18:33]
	ds_read_b128 v[38:41], v232 offset:6656
	s_waitcnt lgkmcnt(0)
	v_mfma_f32_32x32x16_bf16 v[2:17], v[38:41], v[164:167], v[2:17]
	s_nop 15
	s_nop 7
	s_cbranch_vccnz .LBB0_260
	s_cmp_lt_i32 s33, 0
	s_cselect_b64 vcc, -1, 0
	s_nop 5
	v_cndmask_b32_e32 v33, v33, v248, vcc
	v_cndmask_b32_e32 v32, v32, v248, vcc
	v_cndmask_b32_e32 v31, v31, v248, vcc
	v_cndmask_b32_e32 v30, v30, v248, vcc
	v_cndmask_b32_e32 v29, v29, v248, vcc
	v_cndmask_b32_e32 v28, v28, v248, vcc
	v_cndmask_b32_e32 v27, v27, v248, vcc
	v_cndmask_b32_e32 v26, v26, v248, vcc
	v_cndmask_b32_e32 v25, v25, v248, vcc
	v_cndmask_b32_e32 v24, v24, v248, vcc
	v_cndmask_b32_e32 v23, v23, v248, vcc
	v_cndmask_b32_e32 v22, v22, v248, vcc
	v_cndmask_b32_e32 v21, v21, v248, vcc
	v_cndmask_b32_e32 v20, v20, v248, vcc
	v_cndmask_b32_e32 v19, v19, v248, vcc
	v_cndmask_b32_e32 v18, v18, v248, vcc
	v_cndmask_b32_e32 v17, v17, v248, vcc
	v_cndmask_b32_e32 v16, v16, v248, vcc
	v_cndmask_b32_e32 v15, v15, v248, vcc
	v_cndmask_b32_e32 v14, v14, v248, vcc
	v_cndmask_b32_e32 v13, v13, v248, vcc
	v_cndmask_b32_e32 v12, v12, v248, vcc
	v_cndmask_b32_e32 v11, v11, v248, vcc
	v_cndmask_b32_e32 v10, v10, v248, vcc
	v_cndmask_b32_e32 v9, v9, v248, vcc
	v_cndmask_b32_e32 v8, v8, v248, vcc
	v_cndmask_b32_e32 v7, v7, v248, vcc
	v_cndmask_b32_e32 v6, v6, v248, vcc
	v_cndmask_b32_e32 v5, v5, v248, vcc
	v_cndmask_b32_e32 v4, v4, v248, vcc
	v_cndmask_b32_e32 v3, v3, v248, vcc
	v_cndmask_b32_e32 v2, v2, v248, vcc
; __device__ __forceinline__ float max3f(float a,float b,float c){float r;asm("v_max3_f32 %0, %1, %2, %3":"=v"(r):"v"(a),"v"(b),"v"(c));return r;}
; __device__ __forceinline__ float max2f(float a,float b){float r;asm("v_max_f32_e32 %0, %1, %2":"=v"(r):"v"(a),"v"(b));return r;}
; #define WAIT_BAR(N) asm volatile("s_waitcnt vmcnt(" #N ") lgkmcnt(0)\n\ts_barrier":::"memory")
;   #define DMA_K(t,slot) glds16(ksrc+(long)(t)*KVBLK*DM,(unsigned)__builtin_amdgcn_readfirstlane(kdst+(slot)))
;   #define DMA_V(t,slot) do{ glds16(vsrc+(long)(t)*KVBLK*DM,(unsigned)__builtin_amdgcn_readfirstlane(vdst+2*(slot))); glds16(vsrc+(long)(t)*KVBLK*DM+64,(unsigned)__builtin_amdgcn_readfirstlane(vdst+2*(slot)+8192)); }while(0)
;   #define CMASK(P0,P1,t) do{int jb_=(t)-(NT-4); if(jb_>=0)cmask(P0,P1,jb_,qrel,hi);}while(0)
;   #define START(P0,P1) do{ const float rm=rowmax(P0,P1); resc=false; \
;     { const float dl=rm; mhat=fadd_s(mhat,dl); \
;       _Pragma("unroll") for(int r=0;r<16;++r){P0[r]=fsub_s(P0[r],dl);P1[r]=fsub_s(P1[r],dl);} \
;       _Pragma("unroll") for(int r=0;r<16;++r)negm[r]=-mhat; asm volatile("":"+v"(negm)); } \
;     _Pragma("unroll") for(int r=0;r<16;++r)P0[r]=__builtin_amdgcn_exp2f(P0[r]); }while(0)
;   #define CMASK(P0,P1,t) do{}while(0)
; __device__ __forceinline__ float rowmax(const f32x16&p0,const f32x16&p1){
;   float a=max3f(p0[0],p0[1],p1[0]),b=max3f(p0[2],p0[3],p1[1]);a=max3f(a,p1[2],p1[3]);
;   #pragma unroll
;   for(int r=4;r<16;r+=4){a=max3f(a,p0[r],p0[r+1]);b=max3f(b,p0[r+2],p0[r+3]);a=max3f(a,p1[r],p1[r+1]);b=max3f(b,p1[r+2],p1[r+3]);}
;   const float m=max2f(a,b);
;   auto rr=__builtin_amdgcn_permlane32_swap(__float_as_uint(m),__float_as_uint(m),false,false);
;   return max2f(__uint_as_float(rr[0]),__uint_as_float(rr[1]));
; }
; template<int THRL> __device__ __forceinline__ void attn_unit(int b,int hq,int vcol,int qb,const bf16*Q,const bf16*__restrict__ K,const bf16*__restrict__ V,bf16*O,char*shm){
;     ...
;   f32x16 pA0,pA1,pB0,pB1;
;   int sl_prev=0,sl_cur=0,sl_next=SLOTB;
;     ...
;   DMA_K(2,2*SLOTB);
;   WAIT_BAR(4);
;   qkt(pA0,pA1,Kbase,qr,negm,r32,hi);asm volatile("s_nop 15\n\ts_nop 7":"+v"(pA0),"+v"(pA1));CMASK(pA0,pA1,0);
;   START(pA0,pA1);
;   _Pragma("unroll") for(int r=0;r<16;++r)pA1[r]=__builtin_amdgcn_exp2f(pA1[r]);
;   WAIT_BAR(0);
;   DMA_K(3,0);DMA_V(1,SLOTB);
;   ROT();
;   kload8(kf,kp0+sl_cur);
;   WAIT_BAR(3);
.LBB0_260:
	v_max3_f32 v0, v18, v19, v2
	v_max3_f32 v37, v20, v21, v3
	v_lshl_add_u64 v[38:39], v[238:239], 0, s[72:73]
	v_max3_f32 v0, v0, v4, v5
	v_max3_f32 v37, v37, v24, v25
	s_cmp_lg_u32 0, -1
	v_max3_f32 v0, v0, v22, v23
	v_max3_f32 v37, v37, v8, v9
	s_nop 0
	v_max3_f32 v0, v0, v6, v7
	v_max3_f32 v37, v37, v28, v29
	s_nop 0
	v_max3_f32 v0, v0, v26, v27
	v_max3_f32 v37, v37, v12, v13
	s_nop 0
	v_max3_f32 v0, v0, v10, v11
	v_max3_f32 v37, v37, v32, v33
	s_nop 0
	v_max3_f32 v0, v0, v30, v31
	v_max3_f32 v37, v37, v16, v17
	s_nop 0
	v_max3_f32 v0, v0, v14, v15
	s_nop 0
	v_max_f32_e32 v0, v0, v37
	s_nop 0
	v_mov_b32_e32 v37, v0
	s_nop 1
	v_permlane32_swap_b32_e32 v0, v37
	v_max_f32_e32 v37, v0, v37
	s_nop 0
	v_add_f32_e32 v227, v1, v37
	v_sub_f32_e32 v18, v18, v37
	v_sub_f32_e32 v0, v2, v37
	v_sub_f32_e32 v19, v19, v37
	v_sub_f32_e32 v2, v3, v37
	v_sub_f32_e32 v20, v20, v37
	s_nop 0
	v_xor_b32_e32 v80, 0x80000000, v227
	v_mov_b32_e32 v81, v80
	v_mov_b32_e32 v82, v80
	v_mov_b32_e32 v83, v80
	v_mov_b32_e32 v84, v80
	v_mov_b32_e32 v85, v80
	v_mov_b32_e32 v86, v80
	v_mov_b32_e32 v87, v80
	v_mov_b32_e32 v88, v80
	v_mov_b32_e32 v89, v80
	v_mov_b32_e32 v90, v80
	v_mov_b32_e32 v91, v80
	v_mov_b32_e32 v92, v80
	v_mov_b32_e32 v93, v80
	v_mov_b32_e32 v94, v80
	v_mov_b32_e32 v95, v80
	s_waitcnt vmcnt(0) lgkmcnt(0)
	s_barrier
	s_mov_b32 m0, s22
	s_nop 0
	global_load_lds_dwordx4 v[38:39], off
	s_cselect_b32 s3, 0, 0
	s_add_i32 s4, s3, s2
	v_lshl_add_u64 v[38:39], v[34:35], 0, s[94:95]
	s_add_i32 s2, s4, 0xa000
	s_mov_b32 m0, s2
	s_nop 0
	global_load_lds_dwordx4 v[38:39], off
	s_mov_b64 s[2:3], 0x20080
	v_lshl_add_u64 v[34:35], v[34:35], 0, s[2:3]
	s_add_i32 s4, s4, 0xc000
	s_mov_b32 m0, s4
	s_nop 0
	global_load_lds_dwordx4 v[34:35], off
	ds_read_b128 v[220:223], v232 offset:8192
	ds_read_b128 v[216:219], v232 offset:8704
	ds_read_b128 v[212:215], v232 offset:10240
	ds_read_b128 v[208:211], v232 offset:10752
	ds_read_b128 v[204:207], v232 offset:12288
	ds_read_b128 v[200:203], v232 offset:12800
	ds_read_b128 v[196:199], v232 offset:14336
	ds_read_b128 v[192:195], v232 offset:14848
	s_waitcnt vmcnt(3) lgkmcnt(0)
	s_barrier
	s_cmp_lt_i32 s65, 4
	v_sub_f32_e32 v3, v4, v37
	v_sub_f32_e32 v21, v21, v37
	v_sub_f32_e32 v4, v5, v37
	v_sub_f32_e32 v22, v22, v37
	v_sub_f32_e32 v5, v6, v37
	v_sub_f32_e32 v23, v23, v37
	v_sub_f32_e32 v6, v7, v37
	v_sub_f32_e32 v24, v24, v37
	v_sub_f32_e32 v7, v8, v37
	v_sub_f32_e32 v25, v25, v37
	v_sub_f32_e32 v8, v9, v37
	v_sub_f32_e32 v26, v26, v37
	v_sub_f32_e32 v9, v10, v37
	v_sub_f32_e32 v27, v27, v37
	v_sub_f32_e32 v10, v11, v37
	v_sub_f32_e32 v28, v28, v37
	v_sub_f32_e32 v11, v12, v37
	v_sub_f32_e32 v29, v29, v37
	v_sub_f32_e32 v12, v13, v37
	v_sub_f32_e32 v30, v30, v37
	v_sub_f32_e32 v13, v14, v37
	v_sub_f32_e32 v31, v31, v37
	v_sub_f32_e32 v14, v15, v37
	v_sub_f32_e32 v32, v32, v37
	v_sub_f32_e32 v15, v16, v37
	v_sub_f32_e32 v33, v33, v37
	v_sub_f32_e32 v16, v17, v37
	s_cbranch_scc1 .LBB0_262
	s_setprio 1

.LBB0_264:
	s_waitcnt lgkmcnt(7)
	v_mfma_f32_32x32x16_bf16 v[144:159], v[220:223], v[184:187], v[80:95]
	v_add_f32_e32 v2, v112, v113
	v_add_f32_e32 v2, v114, v2
	v_add_f32_e32 v2, v115, v2
	s_lshl_b32 s2, s2, 1
	v_add_f32_e32 v2, v116, v2
	v_add_u32_e32 v0, s2, v233
	v_add_f32_e32 v2, v117, v2
	v_cvt_pk_bf16_f32 v188, v112, v113
	v_cvt_pk_bf16_f32 v189, v114, v115
	s_waitcnt lgkmcnt(6)
	v_mfma_f32_32x32x16_bf16 v[128:143], v[216:219], v[184:187], v[80:95]
	v_add_f32_e32 v2, v118, v2
	v_add_f32_e32 v2, v119, v2
	v_add_f32_e32 v2, v120, v2
	v_add_f32_e32 v2, v121, v2
	v_cvt_pk_bf16_f32 v190, v116, v117
	v_cvt_pk_bf16_f32 v191, v118, v119
	s_waitcnt lgkmcnt(5)
	v_mfma_f32_32x32x16_bf16 v[144:159], v[212:215], v[176:179], v[144:159]
	v_add_f32_e32 v2, v122, v2
	v_add_f32_e32 v2, v123, v2
	v_add_f32_e32 v2, v124, v2
	v_add_f32_e32 v2, v125, v2
	v_cvt_pk_bf16_f32 v180, v120, v121
	v_cvt_pk_bf16_f32 v181, v122, v123
	s_waitcnt lgkmcnt(4)
	v_mfma_f32_32x32x16_bf16 v[128:143], v[208:211], v[176:179], v[128:143]
	v_add_f32_e32 v2, v126, v2
	v_add_f32_e32 v2, v127, v2
	v_add_f32_e32 v2, v96, v2
	v_add_f32_e32 v2, v97, v2
	v_cvt_pk_bf16_f32 v182, v124, v125
	v_cvt_pk_bf16_f32 v183, v126, v127
	s_waitcnt lgkmcnt(3)
	v_mfma_f32_32x32x16_bf16 v[144:159], v[204:207], v[172:175], v[144:159]
	v_add_f32_e32 v2, v98, v2
	v_add_f32_e32 v2, v99, v2
	v_add_f32_e32 v2, v100, v2
	v_add_f32_e32 v2, v101, v2
	v_cvt_pk_bf16_f32 v168, v96, v97
	v_cvt_pk_bf16_f32 v169, v98, v99
	s_waitcnt lgkmcnt(2)
	v_mfma_f32_32x32x16_bf16 v[128:143], v[200:203], v[172:175], v[128:143]
	v_add_f32_e32 v2, v102, v2
	v_add_f32_e32 v2, v103, v2
	v_add_f32_e32 v2, v104, v2
	v_add_f32_e32 v2, v105, v2
	v_cvt_pk_bf16_f32 v170, v100, v101
	v_cvt_pk_bf16_f32 v171, v102, v103
	s_waitcnt lgkmcnt(1)
	v_mfma_f32_32x32x16_bf16 v[144:159], v[196:199], v[164:167], v[144:159]
	v_add_f32_e32 v2, v106, v2
	v_add_f32_e32 v2, v107, v2
	v_add_f32_e32 v2, v108, v2
	v_add_f32_e32 v2, v109, v2
	v_cvt_pk_bf16_f32 v160, v104, v105
	v_cvt_pk_bf16_f32 v161, v106, v107
	s_waitcnt lgkmcnt(0)
	v_mfma_f32_32x32x16_bf16 v[128:143], v[192:195], v[164:167], v[128:143]
	v_add_f32_e32 v2, v110, v2
	v_add_f32_e32 v2, v111, v2
	v_add_f32_e32 v102, 0, v2
	v_cvt_pk_bf16_f32 v162, v108, v109
	v_cvt_pk_bf16_f32 v163, v110, v111
	ds_read_b64_tr_b16 v[96:97], v0 offset:24576
	ds_read_b64_tr_b16 v[98:99], v0 offset:25088
	ds_read_b64_tr_b16 v[10:11], v0 offset:28672
	ds_read_b64_tr_b16 v[12:13], v0 offset:29184
	ds_read_b64_tr_b16 v[6:7], v0 offset:32768
	ds_read_b64_tr_b16 v[8:9], v0 offset:33280
	ds_read_b64_tr_b16 v[2:3], v0 offset:36864
	ds_read_b64_tr_b16 v[4:5], v0 offset:37376
	v_lshl_add_u64 v[208:209], v[238:239], 0, s[54:55]
	v_lshl_add_u64 v[14:15], v[208:209], 0, s[74:75]
	s_add_i32 s2, s4, s22
	s_mov_b32 m0, s2
	s_nop 0
	global_load_lds_dwordx4 v[14:15], off
	v_lshl_add_u64 v[14:15], v[242:243], 0, s[54:55]
	v_lshl_add_u64 v[100:101], v[14:15], 0, s[66:67]
	s_lshl_b32 s2, s96, 1
	s_add_i32 s2, s2, s23
	s_mov_b32 m0, s2
	s_nop 0
	global_load_lds_dwordx4 v[100:101], off
	v_lshl_add_u64 v[100:101], v[14:15], 0, s[84:85]
	s_addk_i32 s2, 0x2000
	s_mov_b32 m0, s2
	s_nop 0
	global_load_lds_dwordx4 v[100:101], off
	v_max_f32_e32 v100, v145, v145
	v_max_f32_e32 v101, v144, v144
	v_max_f32_e32 v100, v101, v100
	v_max3_f32 v101, v146, v147, v129
	v_max3_f32 v100, v100, v128, v130
	v_max3_f32 v100, v100, v131, v148
	v_max3_f32 v101, v101, v150, v151
	v_max3_f32 v100, v100, v149, v132
	v_max3_f32 v101, v101, v134, v135
	v_max3_f32 v100, v100, v133, v152
	v_max3_f32 v101, v101, v154, v155
	v_max3_f32 v100, v100, v153, v136
	v_max3_f32 v101, v101, v138, v139
	v_max3_f32 v100, v100, v137, v156
	v_max3_f32 v101, v101, v158, v159
	v_max3_f32 v100, v100, v157, v140
	v_max3_f32 v101, v101, v142, v143
	v_max3_f32 v100, v100, v141, v101
	v_mov_b32_e32 v101, v100
	s_nop 1
	v_permlane32_swap_b32_e32 v100, v101
	v_max_f32_e32 v101, v101, v101
	v_max_f32_e32 v100, v100, v100
	v_max_f32_e32 v100, v100, v101
	v_cmp_lt_f32_e32 vcc, s11, v100
	s_cmp_lg_u64 vcc, 0
	v_add_f32_e32 v210, v235, v102
	s_cselect_b64 s[46:47], -1, 0
	s_cbranch_vccnz .LBB0_272

.LBB0_267:
	s_add_i32 s2, s96, 0x2000
	s_cmpk_lg_i32 s96, 0x4000
	s_cselect_b32 s24, s2, 0
	v_mfma_f32_32x32x16_bf16 v[112:127], v[96:99], v[184:187], v[80:95]
	v_add_f32_e32 v100, v144, v145
	v_add_f32_e32 v100, v146, v100
	v_add_f32_e32 v100, v147, v100
	s_lshl_b32 s2, s4, 1
	v_add_f32_e32 v100, v148, v100
	v_add_u32_e32 v229, s2, v233
	v_add_f32_e32 v96, v149, v100
	v_cvt_pk_bf16_f32 v188, v144, v145
	v_cvt_pk_bf16_f32 v189, v146, v147
	s_nop 0
	v_add_f32_e32 v96, v150, v96
	v_add_f32_e32 v96, v151, v96
	v_add_f32_e32 v96, v152, v96
	v_add_f32_e32 v144, v153, v96
	v_mfma_f32_32x32x16_bf16 v[96:111], v[200:203], v[184:187], v[80:95]
	v_cvt_pk_bf16_f32 v190, v148, v149
	v_cvt_pk_bf16_f32 v191, v150, v151
	v_mfma_f32_32x32x16_bf16 v[112:127], v[204:207], v[176:179], v[112:127]
	v_add_f32_e32 v144, v154, v144
	v_add_f32_e32 v144, v155, v144
	v_add_f32_e32 v144, v156, v144
	v_add_f32_e32 v144, v157, v144
	v_cvt_pk_bf16_f32 v180, v152, v153
	v_cvt_pk_bf16_f32 v181, v154, v155
	v_mfma_f32_32x32x16_bf16 v[96:111], v[196:199], v[176:179], v[96:111]
	v_add_f32_e32 v144, v158, v144
	v_add_f32_e32 v144, v159, v144
	v_add_f32_e32 v144, v128, v144
	v_add_f32_e32 v144, v129, v144
	v_cvt_pk_bf16_f32 v182, v156, v157
	v_cvt_pk_bf16_f32 v183, v158, v159
	v_mfma_f32_32x32x16_bf16 v[112:127], v[192:195], v[172:175], v[112:127]
	v_add_f32_e32 v144, v130, v144
	v_add_f32_e32 v144, v131, v144
	v_add_f32_e32 v144, v132, v144
	v_add_f32_e32 v144, v133, v144
	v_cvt_pk_bf16_f32 v168, v128, v129
	v_cvt_pk_bf16_f32 v169, v130, v131
	v_mfma_f32_32x32x16_bf16 v[96:111], v[10:13], v[172:175], v[96:111]
	v_add_f32_e32 v10, v134, v144
	v_add_f32_e32 v10, v135, v10
	v_add_f32_e32 v10, v136, v10
	v_add_f32_e32 v10, v137, v10
	v_cvt_pk_bf16_f32 v170, v132, v133
	v_cvt_pk_bf16_f32 v171, v134, v135
	v_mfma_f32_32x32x16_bf16 v[112:127], v[6:9], v[164:167], v[112:127]
	v_add_f32_e32 v6, v138, v10
	v_add_f32_e32 v6, v139, v6
	v_add_f32_e32 v6, v140, v6
	v_add_f32_e32 v6, v141, v6
	v_cvt_pk_bf16_f32 v160, v136, v137
	v_cvt_pk_bf16_f32 v161, v138, v139
	v_mfma_f32_32x32x16_bf16 v[96:111], v[2:5], v[164:167], v[96:111]
	v_add_f32_e32 v2, v142, v6
	v_add_f32_e32 v2, v143, v2
	v_add_f32_e32 v134, 0, v2
	v_cvt_pk_bf16_f32 v162, v140, v141
	v_cvt_pk_bf16_f32 v163, v142, v143
	ds_read_b64_tr_b16 v[128:129], v229 offset:24576
	ds_read_b64_tr_b16 v[130:131], v229 offset:25088
	ds_read_b64_tr_b16 v[10:11], v229 offset:28672
	ds_read_b64_tr_b16 v[12:13], v229 offset:29184
	ds_read_b64_tr_b16 v[6:7], v229 offset:32768
	ds_read_b64_tr_b16 v[8:9], v229 offset:33280
	ds_read_b64_tr_b16 v[2:3], v229 offset:36864
	ds_read_b64_tr_b16 v[4:5], v229 offset:37376
	s_mov_b64 s[2:3], 0xa0000
	v_lshl_add_u64 v[132:133], v[208:209], 0, s[2:3]
	s_add_i32 s2, s96, s22
	s_mov_b32 m0, s2
	s_nop 0
	global_load_lds_dwordx4 v[132:133], off
	s_mov_b64 s[2:3], 0xfe60000
	v_lshl_add_u64 v[132:133], v[14:15], 0, s[2:3]
	s_lshl_b32 s2, s24, 1
	s_add_i32 s4, s2, s23
	s_mov_b32 m0, s4
	s_nop 0
	global_load_lds_dwordx4 v[132:133], off
	s_mov_b64 s[2:3], 0xfe60080
	v_lshl_add_u64 v[14:15], v[14:15], 0, s[2:3]
	s_add_i32 s2, s4, 0x2000
	s_mov_b32 m0, s2
	s_nop 0
	global_load_lds_dwordx4 v[14:15], off
	v_max_f32_e32 v14, v113, v113
	v_max_f32_e32 v15, v112, v112
	v_max_f32_e32 v14, v15, v14
	v_max3_f32 v15, v114, v115, v97
	v_max3_f32 v14, v14, v96, v98
	v_max3_f32 v14, v14, v99, v116
	v_max3_f32 v15, v15, v118, v119
	v_max3_f32 v14, v14, v117, v100
	v_max3_f32 v15, v15, v102, v103
	v_max3_f32 v14, v14, v101, v120
	v_max3_f32 v15, v15, v122, v123
	v_max3_f32 v14, v14, v121, v104
	v_max3_f32 v15, v15, v106, v107
	v_max3_f32 v14, v14, v105, v124
	v_max3_f32 v15, v15, v126, v127
	v_max3_f32 v14, v14, v125, v108
	v_max3_f32 v15, v15, v110, v111
	v_max3_f32 v14, v14, v109, v15
	v_mov_b32_e32 v15, v14
	s_nop 1
	v_permlane32_swap_b32_e32 v14, v15
	v_max_f32_e32 v15, v15, v15
	v_max_f32_e32 v14, v14, v14
	v_max_f32_e32 v14, v14, v15
	v_cmp_lt_f32_e32 vcc, s11, v14
	s_cmp_lg_u64 vcc, 0
	v_add_f32_e32 v235, v210, v134
	s_cselect_b64 s[46:47], -1, 0
	s_cbranch_vccnz .LBB0_275

; __device__ __forceinline__ void cmask(f32x16&p0,f32x16&p1,int jb,int qrel,int hi){
;   const float NEG=-INFINITY; (void)hi;
;   #pragma unroll
;   for(int r=0;r<16;++r){ if(jb>(qrel>>6)){p0[r]=NEG; p1[r]=NEG;} }
; }
.LBB0_285:
	s_waitcnt lgkmcnt(7)
	v_mfma_f32_32x32x16_bf16 v[144:159], v[220:223], v[184:187], v[80:95]
	v_add_f32_e32 v2, v112, v113
	v_add_f32_e32 v2, v114, v2
	v_add_f32_e32 v2, v115, v2
	s_lshl_b32 s2, s96, 1
	v_add_f32_e32 v2, v116, v2
	v_add_u32_e32 v0, s2, v233
	v_add_f32_e32 v2, v117, v2
	v_cvt_pk_bf16_f32 v188, v112, v113
	v_cvt_pk_bf16_f32 v189, v114, v115
	s_waitcnt lgkmcnt(6)
	v_mfma_f32_32x32x16_bf16 v[128:143], v[216:219], v[184:187], v[80:95]
	v_add_f32_e32 v2, v118, v2
	v_add_f32_e32 v2, v119, v2
	v_add_f32_e32 v2, v120, v2
	v_add_f32_e32 v2, v121, v2
	v_cvt_pk_bf16_f32 v190, v116, v117
	v_cvt_pk_bf16_f32 v191, v118, v119
	s_waitcnt lgkmcnt(5)
	v_mfma_f32_32x32x16_bf16 v[144:159], v[212:215], v[176:179], v[144:159]
	v_add_f32_e32 v2, v122, v2
	v_add_f32_e32 v2, v123, v2
	v_add_f32_e32 v2, v124, v2
	v_add_f32_e32 v2, v125, v2
	v_cvt_pk_bf16_f32 v180, v120, v121
	v_cvt_pk_bf16_f32 v181, v122, v123
	s_waitcnt lgkmcnt(4)
	v_mfma_f32_32x32x16_bf16 v[128:143], v[208:211], v[176:179], v[128:143]
	v_add_f32_e32 v2, v126, v2
	v_add_f32_e32 v2, v127, v2
	v_add_f32_e32 v2, v96, v2
	v_add_f32_e32 v2, v97, v2
	v_cvt_pk_bf16_f32 v182, v124, v125
	v_cvt_pk_bf16_f32 v183, v126, v127
	s_waitcnt lgkmcnt(3)
	v_mfma_f32_32x32x16_bf16 v[144:159], v[204:207], v[172:175], v[144:159]
	v_add_f32_e32 v2, v98, v2
	v_add_f32_e32 v2, v99, v2
	v_add_f32_e32 v2, v100, v2
	v_add_f32_e32 v2, v101, v2
	v_cvt_pk_bf16_f32 v168, v96, v97
	v_cvt_pk_bf16_f32 v169, v98, v99
	s_waitcnt lgkmcnt(2)
	v_mfma_f32_32x32x16_bf16 v[128:143], v[200:203], v[172:175], v[128:143]
	v_add_f32_e32 v2, v102, v2
	v_add_f32_e32 v2, v103, v2
	v_add_f32_e32 v2, v104, v2
	v_add_f32_e32 v2, v105, v2
	v_cvt_pk_bf16_f32 v170, v100, v101
	v_cvt_pk_bf16_f32 v171, v102, v103
	s_waitcnt lgkmcnt(1)
	v_mfma_f32_32x32x16_bf16 v[144:159], v[196:199], v[164:167], v[144:159]
	v_add_f32_e32 v2, v106, v2
	v_add_f32_e32 v2, v107, v2
	v_add_f32_e32 v2, v108, v2
	v_add_f32_e32 v2, v109, v2
	v_cvt_pk_bf16_f32 v160, v104, v105
	v_cvt_pk_bf16_f32 v161, v106, v107
	s_waitcnt lgkmcnt(0)
	v_mfma_f32_32x32x16_bf16 v[128:143], v[192:195], v[164:167], v[128:143]
	v_add_f32_e32 v2, v110, v2
	v_add_f32_e32 v2, v111, v2
	v_add_f32_e32 v100, 0, v2
	v_cvt_pk_bf16_f32 v162, v108, v109
	v_cvt_pk_bf16_f32 v163, v110, v111
	ds_read_b64_tr_b16 v[96:97], v0 offset:24576
	ds_read_b64_tr_b16 v[98:99], v0 offset:25088
	ds_read_b64_tr_b16 v[10:11], v0 offset:28672
	ds_read_b64_tr_b16 v[12:13], v0 offset:29184
	ds_read_b64_tr_b16 v[6:7], v0 offset:32768
	ds_read_b64_tr_b16 v[8:9], v0 offset:33280
	ds_read_b64_tr_b16 v[2:3], v0 offset:36864
	ds_read_b64_tr_b16 v[4:5], v0 offset:37376
	s_add_i32 s2, s12, 1
	s_cmp_ge_u32 s2, s68
	s_cselect_b64 s[92:93], -1, 0
	s_and_b64 vcc, exec, s[92:93]
	v_lshl_add_u64 v[242:243], v[238:239], 0, s[94:95]
	s_cbranch_vccnz .LBB0_287
	v_lshl_add_u64 v[102:103], v[242:243], 0, s[72:73]
	s_add_i32 s2, s24, s22
	s_mov_b32 m0, s2
	s_nop 0
	global_load_lds_dwordx4 v[102:103], off
.LBB0_287:
	v_lshl_add_u64 v[240:241], v[14:15], 0, s[94:95]
	s_mov_b64 s[2:3], 0xfe20000
	s_lshl_b32 s4, s25, 1
	v_lshl_add_u64 v[102:103], v[240:241], 0, s[2:3]
	s_add_i32 s40, s4, s23
	s_mov_b32 m0, s40
	s_nop 0
	global_load_lds_dwordx4 v[102:103], off
	s_mov_b64 s[2:3], 0xfe20080
	v_lshl_add_u64 v[102:103], v[240:241], 0, s[2:3]
	s_add_i32 s2, s40, 0x2000
	s_mov_b32 m0, s2
	s_nop 0
	global_load_lds_dwordx4 v[102:103], off
	s_add_i32 s90, s69, s12
	s_add_i32 s2, s90, -2
	s_cmp_lt_i32 s2, 0
	s_cbranch_scc1 .LBB0_289
	s_cmp_gt_i32 s2, s45
	s_cselect_b64 vcc, -1, 0
	v_cndmask_b32_e32 v159, v159, v248, vcc
	v_cndmask_b32_e32 v158, v158, v248, vcc
	v_cndmask_b32_e32 v157, v157, v248, vcc
	v_cndmask_b32_e32 v156, v156, v248, vcc
	v_cndmask_b32_e32 v155, v155, v248, vcc
	v_cndmask_b32_e32 v154, v154, v248, vcc
	v_cndmask_b32_e32 v153, v153, v248, vcc
	v_cndmask_b32_e32 v152, v152, v248, vcc
	v_cndmask_b32_e32 v151, v151, v248, vcc
	v_cndmask_b32_e32 v150, v150, v248, vcc
	v_cndmask_b32_e32 v149, v149, v248, vcc
	v_cndmask_b32_e32 v148, v148, v248, vcc
	v_cndmask_b32_e32 v147, v147, v248, vcc
	v_cndmask_b32_e32 v146, v146, v248, vcc
	v_cndmask_b32_e32 v145, v145, v248, vcc
	v_cndmask_b32_e32 v144, v144, v248, vcc
	v_cndmask_b32_e32 v143, v143, v248, vcc
	v_cndmask_b32_e32 v142, v142, v248, vcc
	v_cndmask_b32_e32 v141, v141, v248, vcc
	v_cndmask_b32_e32 v140, v140, v248, vcc
	v_cndmask_b32_e32 v139, v139, v248, vcc
	v_cndmask_b32_e32 v138, v138, v248, vcc
	v_cndmask_b32_e32 v137, v137, v248, vcc
	v_cndmask_b32_e32 v136, v136, v248, vcc
	v_cndmask_b32_e32 v135, v135, v248, vcc
	v_cndmask_b32_e32 v134, v134, v248, vcc
	v_cndmask_b32_e32 v133, v133, v248, vcc
	v_cndmask_b32_e32 v132, v132, v248, vcc
	v_cndmask_b32_e32 v131, v131, v248, vcc
	v_cndmask_b32_e32 v130, v130, v248, vcc
	v_cndmask_b32_e32 v129, v129, v248, vcc
	v_cndmask_b32_e32 v128, v128, v248, vcc

.LBB0_294:
	v_mfma_f32_32x32x16_bf16 v[112:127], v[220:223], v[184:187], v[80:95]
	v_add_f32_e32 v2, v144, v145
	v_add_f32_e32 v2, v146, v2
	v_add_f32_e32 v2, v147, v2
	s_lshl_b32 s2, s24, 1
	v_add_f32_e32 v2, v148, v2
	v_add_u32_e32 v229, s2, v233
	v_add_f32_e32 v2, v149, v2
	v_cvt_pk_bf16_f32 v188, v144, v145
	v_cvt_pk_bf16_f32 v189, v146, v147
	v_mfma_f32_32x32x16_bf16 v[96:111], v[216:219], v[184:187], v[80:95]
	v_add_f32_e32 v2, v150, v2
	v_add_f32_e32 v2, v151, v2
	v_add_f32_e32 v2, v152, v2
	v_add_f32_e32 v2, v153, v2
	v_cvt_pk_bf16_f32 v190, v148, v149
	v_cvt_pk_bf16_f32 v191, v150, v151
	v_mfma_f32_32x32x16_bf16 v[112:127], v[212:215], v[176:179], v[112:127]
	v_add_f32_e32 v2, v154, v2
	v_add_f32_e32 v2, v155, v2
	v_add_f32_e32 v2, v156, v2
	v_add_f32_e32 v2, v157, v2
	v_cvt_pk_bf16_f32 v180, v152, v153
	v_cvt_pk_bf16_f32 v181, v154, v155
	v_mfma_f32_32x32x16_bf16 v[96:111], v[208:211], v[176:179], v[96:111]
	v_add_f32_e32 v2, v158, v2
	v_add_f32_e32 v2, v159, v2
	v_add_f32_e32 v2, v128, v2
	v_add_f32_e32 v2, v129, v2
	v_cvt_pk_bf16_f32 v182, v156, v157
	v_cvt_pk_bf16_f32 v183, v158, v159
	v_mfma_f32_32x32x16_bf16 v[112:127], v[204:207], v[172:175], v[112:127]
	v_add_f32_e32 v2, v130, v2
	v_add_f32_e32 v2, v131, v2
	v_add_f32_e32 v2, v132, v2
	v_add_f32_e32 v2, v133, v2
	v_cvt_pk_bf16_f32 v168, v128, v129
	v_cvt_pk_bf16_f32 v169, v130, v131
	v_mfma_f32_32x32x16_bf16 v[96:111], v[200:203], v[172:175], v[96:111]
	v_add_f32_e32 v2, v134, v2
	v_add_f32_e32 v2, v135, v2
	v_add_f32_e32 v2, v136, v2
	v_add_f32_e32 v2, v137, v2
	v_cvt_pk_bf16_f32 v170, v132, v133
	v_cvt_pk_bf16_f32 v171, v134, v135
	v_mfma_f32_32x32x16_bf16 v[112:127], v[196:199], v[164:167], v[112:127]
	v_add_f32_e32 v2, v138, v2
	v_add_f32_e32 v2, v139, v2
	v_add_f32_e32 v2, v140, v2
	v_add_f32_e32 v2, v141, v2
	v_cvt_pk_bf16_f32 v160, v136, v137
	v_cvt_pk_bf16_f32 v161, v138, v139
	v_mfma_f32_32x32x16_bf16 v[96:111], v[192:195], v[164:167], v[96:111]
	v_add_f32_e32 v2, v142, v2
	v_add_f32_e32 v2, v143, v2
	v_add_f32_e32 v132, 0, v2
	v_cvt_pk_bf16_f32 v162, v140, v141
	v_cvt_pk_bf16_f32 v163, v142, v143
	ds_read_b64_tr_b16 v[128:129], v229 offset:24576
	ds_read_b64_tr_b16 v[130:131], v229 offset:25088
	ds_read_b64_tr_b16 v[10:11], v229 offset:28672
	ds_read_b64_tr_b16 v[12:13], v229 offset:29184
	ds_read_b64_tr_b16 v[6:7], v229 offset:32768
	ds_read_b64_tr_b16 v[8:9], v229 offset:33280
	ds_read_b64_tr_b16 v[2:3], v229 offset:36864
	ds_read_b64_tr_b16 v[4:5], v229 offset:37376
	s_add_i32 s2, s12, 2
	s_cmp_ge_u32 s2, s68
	s_cselect_b64 s[96:97], -1, 0
	s_and_b64 vcc, exec, s[96:97]
	s_cbranch_vccnz .LBB0_296
	v_lshl_add_u64 v[134:135], v[242:243], 0, s[74:75]
	s_add_i32 s3, s25, s22
	s_mov_b32 m0, s3
	s_nop 0
	global_load_lds_dwordx4 v[134:135], off
.LBB0_296:
	s_add_i32 s3, s25, 0x2000
	s_cmpk_lg_i32 s25, 0x4000
	s_cselect_b32 s24, s3, 0
	s_cmp_lt_u32 s12, s68
	s_cselect_b64 s[48:49], -1, 0
	s_cmp_ge_u32 s12, s68
	s_cbranch_scc1 .LBB0_298
	s_lshl_b32 s3, s24, 1
	s_add_i32 s3, s3, s23
	v_lshl_add_u64 v[134:135], v[240:241], 0, s[66:67]
	s_mov_b32 m0, s3
	s_nop 0
	global_load_lds_dwordx4 v[134:135], off
	v_lshl_add_u64 v[136:137], v[240:241], 0, s[84:85]
	s_addk_i32 s3, 0x2000
	s_mov_b32 m0, s3
	s_nop 0
	global_load_lds_dwordx4 v[136:137], off

; __device__ __forceinline__ unsigned xb_add(unsigned* p, unsigned v) { return __hip_atomic_fetch_add(p, v, __ATOMIC_RELAXED, __HIP_MEMORY_SCOPE_AGENT); }
; __device__ __forceinline__ void xcd_barrier(const XcdBarrier& b) {
;     ...
;     if (threadIdx.x == 0) {
;         unsigned* bar = b.bar;
;         __builtin_amdgcn_s_waitcnt(0);
;         unsigned nloc = b.st[0], nx = b.st[1];
;         if (nloc == 0u) { xcd_barrier_complete(bar, b.x, nloc, nx); b.st[0] = nloc; b.st[1] = nx; }
;         const unsigned old = xb_add(&bar[XB_XSUB(b.x)], 1u);
;         const unsigned gen = old / nloc;
;         if (old + 1u == (gen + 1u) * nloc) {
.LBB0_441:
	s_waitcnt vmcnt(0)
	s_barrier
	s_mov_b64 s[2:3], exec
	v_readlane_b32 s12, v253, 36
	v_readlane_b32 s13, v253, 37
	s_and_b64 s[12:13], s[2:3], s[12:13]
	s_mov_b64 exec, s[12:13]
	s_cbranch_execz .LBB0_493
	s_cmp_lg_u32 s98, 0
	s_cbranch_scc0 .Lgb_full_493
	v_readlane_b32 s4, v253, 1
	v_readlane_b32 s12, v253, 56
	v_readlane_b32 s13, v253, 57
	s_add_i32 s99, s99, 4
	s_nop 2
	s_and_b32 s4, s4, 63
	s_lshl_b32 s4, s4, 7
	s_add_i32 s4, s4, 0x3e00
	v_mov_b32_e32 v2, s4
	s_mov_b32 s1, 0
	s_nop 1
	global_atomic_add v5, v2, v234, s[12:13] sc0
	v_mov_b32_e32 v4, 0x5e00
	global_atomic_add v4, v234, s[12:13]
	s_waitcnt vmcnt(1)
	v_readfirstlane_b32 s4, v5
	s_nop 3
	s_add_i32 s4, s4, 1
	s_cmp_ge_u32 s4, s99
	s_cbranch_scc1 .Lgb_grp_ok_493

; __device__ __forceinline__ unsigned xb_add(unsigned* p, unsigned v) { return __hip_atomic_fetch_add(p, v, __ATOMIC_RELAXED, __HIP_MEMORY_SCOPE_AGENT); }
; __device__ __forceinline__ void xcd_barrier(const XcdBarrier& b) {
;     ...
;     if (threadIdx.x == 0) {
;         unsigned* bar = b.bar;
;         __builtin_amdgcn_s_waitcnt(0);
;         unsigned nloc = b.st[0], nx = b.st[1];
;         if (nloc == 0u) { xcd_barrier_complete(bar, b.x, nloc, nx); b.st[0] = nloc; b.st[1] = nx; }
;         const unsigned old = xb_add(&bar[XB_XSUB(b.x)], 1u);
;         const unsigned gen = old / nloc;
;         if (old + 1u == (gen + 1u) * nloc) {
.LBB0_517:
	s_waitcnt vmcnt(0)
	s_barrier
	s_mov_b64 s[2:3], exec
	v_readlane_b32 s12, v253, 36
	v_readlane_b32 s13, v253, 37
	s_and_b64 s[12:13], s[2:3], s[12:13]
	s_mov_b64 exec, s[12:13]
	s_cbranch_execz .LBB0_569
	s_cmp_lg_u32 s98, 0
	s_cbranch_scc0 .Lgb_full_569
	v_readlane_b32 s4, v253, 1
	v_readlane_b32 s12, v253, 56
	v_readlane_b32 s13, v253, 57
	s_add_i32 s99, s99, 4
	s_nop 2
	s_and_b32 s4, s4, 63
	s_lshl_b32 s4, s4, 7
	s_add_i32 s4, s4, 0x3e00
	v_mov_b32_e32 v2, s4
	s_mov_b32 s1, 0
	s_nop 1
	global_atomic_add v5, v2, v234, s[12:13] sc0
	s_waitcnt vmcnt(0)
	v_readfirstlane_b32 s4, v5
	s_nop 3
	s_add_i32 s4, s4, 1
	s_cmp_ge_u32 s4, s99
	s_cbranch_scc1 .Lgb_grp_ok_569

; __device__ __forceinline__ unsigned xb_add(unsigned* p, unsigned v) { return __hip_atomic_fetch_add(p, v, __ATOMIC_RELAXED, __HIP_MEMORY_SCOPE_AGENT); }
; __device__ __forceinline__ void xcd_barrier(const XcdBarrier& b) {
;     ...
;     if (threadIdx.x == 0) {
;         unsigned* bar = b.bar;
;         __builtin_amdgcn_s_waitcnt(0);
;         unsigned nloc = b.st[0], nx = b.st[1];
;         if (nloc == 0u) { xcd_barrier_complete(bar, b.x, nloc, nx); b.st[0] = nloc; b.st[1] = nx; }
;         const unsigned old = xb_add(&bar[XB_XSUB(b.x)], 1u);
;         const unsigned gen = old / nloc;
;         if (old + 1u == (gen + 1u) * nloc) {
.LBB0_628:
	s_waitcnt vmcnt(0)
	s_waitcnt vmcnt(0)
	s_barrier
	s_mov_b64 s[16:17], exec
	v_readlane_b32 s12, v253, 36
	v_readlane_b32 s13, v253, 37
	s_and_b64 s[12:13], s[16:17], s[12:13]
	s_mov_b64 exec, s[12:13]
	s_cbranch_execz .LBB0_680
	s_cmp_lg_u32 s98, 0
	s_cbranch_scc0 .Lgb_full_680
	v_readlane_b32 s4, v253, 1
	v_readlane_b32 s12, v253, 56
	v_readlane_b32 s13, v253, 57
	s_add_i32 s99, s99, 4
	s_nop 2
	s_and_b32 s4, s4, 63
	s_lshl_b32 s4, s4, 7
	s_add_i32 s4, s4, 0x3e00
	v_mov_b32_e32 v2, s4
	s_mov_b32 s1, 0
	s_nop 1
	global_atomic_add v5, v2, v234, s[12:13] sc0
	v_mov_b32_e32 v4, 0x5ec0
	global_atomic_add v4, v234, s[12:13]
	s_waitcnt vmcnt(1)
	v_readfirstlane_b32 s4, v5
	s_nop 3
	s_add_i32 s4, s4, 1
	s_cmp_ge_u32 s4, s99
	s_cbranch_scc1 .Lgb_grp_ok_680

; __device__ __forceinline__ unsigned xb_add(unsigned* p, unsigned v) { return __hip_atomic_fetch_add(p, v, __ATOMIC_RELAXED, __HIP_MEMORY_SCOPE_AGENT); }
; __device__ __forceinline__ void xcd_barrier(const XcdBarrier& b) {
;     ...
;     if (threadIdx.x == 0) {
;         unsigned* bar = b.bar;
;         __builtin_amdgcn_s_waitcnt(0);
;         unsigned nloc = b.st[0], nx = b.st[1];
;         if (nloc == 0u) { xcd_barrier_complete(bar, b.x, nloc, nx); b.st[0] = nloc; b.st[1] = nx; }
;         const unsigned old = xb_add(&bar[XB_XSUB(b.x)], 1u);
;         const unsigned gen = old / nloc;
;         if (old + 1u == (gen + 1u) * nloc) {
.LBB0_708:
	s_waitcnt vmcnt(0)
	s_barrier
	s_mov_b64 s[16:17], exec
	v_readlane_b32 s12, v253, 36
	v_readlane_b32 s13, v253, 37
	s_and_b64 s[12:13], s[16:17], s[12:13]
	s_mov_b64 exec, s[12:13]
	s_cbranch_execz .LBB0_137
	s_cmp_lg_u32 s98, 0
	s_cbranch_scc0 .Lgb_full_137
	v_readlane_b32 s4, v253, 1
	v_readlane_b32 s12, v253, 56
	v_readlane_b32 s13, v253, 57
	s_add_i32 s99, s99, 4
	s_nop 2
	s_and_b32 s4, s4, 63
	s_lshl_b32 s4, s4, 7
	s_add_i32 s4, s4, 0x3e00
	v_mov_b32_e32 v2, s4
	s_mov_b32 s1, 0
	s_nop 1
	global_atomic_add v5, v2, v234, s[12:13] sc0
	v_mov_b32_e32 v4, 0x5e80
	global_atomic_add v4, v234, s[12:13]
	s_waitcnt vmcnt(1)
	v_readfirstlane_b32 s4, v5
	s_nop 3
	s_add_i32 s4, s4, 1
	s_cmp_ge_u32 s4, s99
	s_cbranch_scc1 .Lgb_grp_ok_137
